# P0 row loop: p-row load of prompt rows issued with the x-row loads (second per-row round trip removed); code padded to keep downstream placement
# baseline (speedup 1.0000x reference)
; __device__ __forceinline__ unsigned pk2(float lo, float hi) { f32x2 v = {lo, hi}; bf16x2_t b = __builtin_convertvector(v, bf16x2_t); return __builtin_bit_cast(unsigned, b); }
; __device__ __forceinline__ void p0_prologue(const Args& a, LAS unsigned char* lds, int vcu, int G, int tid, int lane, int wave) {
;     ...
;         u32x2 o; o.x = pk2(v.x, v.y); o.y = pk2(v.z, v.w);
;         ((u32x2*)((bf16*)(ws + WS_PB) + (size_t)m * DPLE))[lane] = o;
.Lp0b_fin:
	v_lshl_add_u64 v[2:3], v[16:17], 0, s[2:3]
	global_store_dwordx2 v[2:3], v[0:1], off

; __device__ __forceinline__ unsigned pk2(float lo, float hi) { f32x2 v = {lo, hi}; bf16x2_t b = __builtin_convertvector(v, bf16x2_t); return __builtin_bit_cast(unsigned, b); }
; __device__ __forceinline__ void rms_row_to_bf16(const float* xrow, const float* gain, bf16* orow, int lane) {
;     f32x4 v[4]; float s = 0.f;
; #pragma unroll
;     for (int j = 0; j < 4; ++j) { v[j] = xrow ? ((const f32x4*)xrow)[lane + 64 * j] : (f32x4){0.f, 0.f, 0.f, 0.f}; s += (v[j].x * v[j].x + v[j].y * v[j].y) + (v[j].z * v[j].z + v[j].w * v[j].w); }
;     const float rstd = 1.f / sqrtf(wave_sum(s) * (1.f / DM) + EPS);
; #pragma unroll
;     for (int j = 0; j < 4; ++j) { const f32x4 g = ((const f32x4*)gain)[lane + 64 * j];
;         u32x2 o; o.x = pk2(v[j].x * rstd * g.x, v[j].y * rstd * g.y); o.y = pk2(v[j].z * rstd * g.z, v[j].w * rstd * g.w);
;         ((u32x2*)orow)[lane + 64 * j] = o; }
; __device__ __forceinline__ void p0_prologue(const Args& a, LAS unsigned char* lds, int vcu, int G, int tid, int lane, int wave) {
;     ...
;     for (int qq = 0; qq < 2; ++qq) { const int m = m0 + qq * NGW; if (m >= MT) break;
;         rms_row_to_bf16(xrow_ptr(a, m, z), (const float*)a.in[I_F1PRE + z], (bf16*)(ws + WS_XN) + (size_t)m * DM, lane);
;         const float* pr = m < MP ? (const float*)a.in[I_PP + z] + (size_t)m * DPLE : (m < MP + NS ? (const float*)a.in[I_PS + z] + (size_t)(m - MP) * DPLE : nullptr);
;         const f32x4 v = pr ? ((const f32x4*)pr)[lane] : (f32x4){0.f, 0.f, 0.f, 0.f};
;         u32x2 o; o.x = pk2(v.x, v.y); o.y = pk2(v.z, v.w);
;         ((u32x2*)((bf16*)(ws + WS_PB) + (size_t)m * DPLE))[lane] = o;
.LBB0_55:
	s_cmpk_gt_i32 s6, 0x3fff
	s_cbranch_scc1 .Lp0a_nopf
	s_lshl_b64 s[14:15], s[6:7], 10
	s_add_u32 s14, s100, s14
	s_addc_u32 s15, s101, s15
	global_load_dwordx4 v[56:59], v24, s[14:15]
.Lp0a_nopf:
	v_mov_b64_e32 v[26:27], v[40:41]
	v_mov_b64_e32 v[28:29], v[42:43]
	s_waitcnt vmcnt(0)
	v_mul_f32_e32 v25, v9, v9
	v_mul_f32_e32 v30, v11, v11
	v_mul_f32_e32 v31, v1, v1
	v_mul_f32_e32 v32, v3, v3
	v_mul_f32_e32 v33, v13, v13
	v_mul_f32_e32 v34, v15, v15
	v_fmac_f32_e32 v25, v8, v8
	v_fmac_f32_e32 v30, v10, v10
	v_fmac_f32_e32 v31, v0, v0
	v_fmac_f32_e32 v32, v2, v2
	v_mul_f32_e32 v35, v5, v5
	v_mul_f32_e32 v36, v7, v7
	v_fmac_f32_e32 v33, v12, v12
	v_fmac_f32_e32 v34, v14, v14
	v_add_f32_e32 v25, v25, v30
	v_add_f32_e32 v30, v31, v32
	v_fmac_f32_e32 v35, v4, v4
	v_fmac_f32_e32 v36, v6, v6
	v_add_f32_e32 v31, v33, v34
	v_add_f32_e32 v25, v25, v30
	v_add_f32_e32 v32, v35, v36
	v_add_f32_e32 v25, v25, v31
	v_add_f32_e32 v25, v25, v32
	s_ashr_i32 s7, s6, 31
	s_lshl_b64 s[12:13], s[6:7], 11
	v_add_f32_dpp v25, v25, v25 quad_perm:[1,0,3,2] row_mask:0xf bank_mask:0xf bound_ctrl:1
	s_nop 1
	v_add_f32_dpp v25, v25, v25 quad_perm:[2,3,0,1] row_mask:0xf bank_mask:0xf bound_ctrl:1
	s_nop 1
	v_add_f32_dpp v25, v25, v25 row_half_mirror row_mask:0xf bank_mask:0xf bound_ctrl:1
	s_nop 1
	v_add_f32_dpp v25, v25, v25 row_mirror row_mask:0xf bank_mask:0xf bound_ctrl:1
	v_mov_b32_e32 v30, v25
	s_nop 1
	v_permlane16_swap_b32_e32 v25, v30
	v_add_f32_e32 v25, v25, v30
	v_mov_b32_e32 v30, v25
	s_nop 1
	v_permlane32_swap_b32_e32 v25, v30
	v_add_f32_e32 v25, v25, v30
	v_fmamk_f32 v25, v25, 0x3a800000, v22
	v_mul_f32_e32 v30, 0x4f800000, v25
	v_cmp_gt_f32_e32 vcc, s16, v25
	s_nop 1
	v_cndmask_b32_e32 v25, v25, v30, vcc
	v_sqrt_f32_e32 v30, v25
	s_nop 0
	v_add_u32_e32 v31, -1, v30
	v_add_u32_e32 v32, 1, v30
	v_fma_f32 v33, -v31, v30, v25
	v_fma_f32 v34, -v32, v30, v25
	v_cmp_ge_f32_e64 s[2:3], 0, v33
	s_nop 1
	v_cndmask_b32_e64 v30, v30, v31, s[2:3]
	v_cmp_lt_f32_e64 s[2:3], 0, v34
	s_nop 1
	v_cndmask_b32_e64 v30, v30, v32, s[2:3]
	v_mul_f32_e32 v31, 0x37800000, v30
	v_cndmask_b32_e32 v30, v30, v31, vcc
	v_cmp_class_f32_e32 vcc, v25, v23
	s_nop 1
	v_cndmask_b32_e32 v25, v30, v25, vcc
	v_div_scale_f32 v32, s[2:3], v25, v25, 1.0
	v_rcp_f32_e32 v33, v32
	v_div_scale_f32 v34, vcc, 1.0, v25, 1.0
	v_lshl_add_u64 v[30:31], v[20:21], 0, s[12:13]
	v_fma_f32 v35, -v32, v33, 1.0
	v_fmac_f32_e32 v33, v35, v33
	v_mul_f32_e32 v35, v34, v33
	v_fma_f32 v36, -v32, v35, v34
	v_fmac_f32_e32 v35, v36, v33
	v_fma_f32 v32, -v32, v35, v34
	v_div_fmas_f32 v32, v32, v33, v35
	v_div_fixup_f32 v32, v32, v25, 1.0
	v_pk_mul_f32 v[8:9], v[8:9], v[32:33] op_sel_hi:[1,0]
	v_pk_mul_f32 v[10:11], v[10:11], v[32:33] op_sel_hi:[1,0]
	v_pk_mul_f32 v[8:9], v[26:27], v[8:9]
	v_pk_mul_f32 v[10:11], v[28:29], v[10:11]
	v_cvt_pk_bf16_f32 v8, v8, v9
	v_cvt_pk_bf16_f32 v9, v10, v11
	global_store_dwordx2 v[30:31], v[8:9], off
	s_nop 0
	v_mov_b64_e32 v[8:9], v[44:45]
	v_mov_b64_e32 v[10:11], v[46:47]
	v_pk_mul_f32 v[0:1], v[0:1], v[32:33] op_sel_hi:[1,0]
	v_pk_mul_f32 v[2:3], v[2:3], v[32:33] op_sel_hi:[1,0]
	v_pk_mul_f32 v[4:5], v[4:5], v[32:33] op_sel_hi:[1,0]
	v_pk_mul_f32 v[6:7], v[6:7], v[32:33] op_sel_hi:[1,0]
	s_mov_b64 s[12:13], -1
	s_and_b64 vcc, exec, s[10:11]
	v_pk_mul_f32 v[0:1], v[8:9], v[0:1]
	v_pk_mul_f32 v[2:3], v[10:11], v[2:3]
	v_cvt_pk_bf16_f32 v0, v0, v1
	v_cvt_pk_bf16_f32 v1, v2, v3
	global_store_dwordx2 v[30:31], v[0:1], off offset:512
	s_nop 0
	v_mov_b64_e32 v[0:1], v[48:49]
	v_mov_b64_e32 v[2:3], v[50:51]
	v_pk_mul_f32 v[8:9], v[12:13], v[32:33] op_sel_hi:[1,0]
	v_pk_mul_f32 v[10:11], v[14:15], v[32:33] op_sel_hi:[1,0]
	v_pk_mul_f32 v[0:1], v[0:1], v[8:9]
	v_pk_mul_f32 v[2:3], v[2:3], v[10:11]
	v_cvt_pk_bf16_f32 v0, v0, v1
	v_cvt_pk_bf16_f32 v1, v2, v3
	global_store_dwordx2 v[30:31], v[0:1], off offset:1024
	s_nop 0
	v_mov_b64_e32 v[0:1], v[52:53]
	v_mov_b64_e32 v[2:3], v[54:55]
	v_pk_mul_f32 v[0:1], v[4:5], v[0:1]
	v_pk_mul_f32 v[2:3], v[6:7], v[2:3]
	v_cvt_pk_bf16_f32 v0, v0, v1
	v_cvt_pk_bf16_f32 v1, v2, v3
	global_store_dwordx2 v[30:31], v[0:1], off offset:1536
	s_cmpk_gt_i32 s6, 0x3fff
	s_cbranch_scc1 .Lp0a_orig
	v_cvt_pk_bf16_f32 v0, v56, v57
	v_cvt_pk_bf16_f32 v1, v58, v59
	s_lshl_b64 s[2:3], s[6:7], 9
	s_add_i32 s6, s6, s22
	s_branch .Lp0a_fin
	s_nop 0
.Lp0a_orig:
	s_cbranch_vccz .LBB0_58
	s_mov_b64 s[12:13], 0
	s_cmpk_gt_u32 s6, 0x407f
	s_mov_b64 s[2:3], 0
	s_cbranch_scc1 .LBB0_58
	s_load_dwordx2 s[2:3], s[4:5], 0x18
	s_add_i32 s8, s6, 0xffffc000
	s_lshl_b64 s[10:11], s[8:9], 10
	s_waitcnt lgkmcnt(0)
	s_add_u32 s2, s2, s10
	s_addc_u32 s3, s3, s11

; __device__ __forceinline__ const float* xrow_ptr(const Args& a, int m, int z) {
;     if (m < MP) return (const float*)a.in[I_XP + z] + (size_t)m * DM;
;     if (m < MP + NS) return (const float*)a.in[I_XS + z] + (size_t)(m - MP) * DM;
;     return nullptr;
; __device__ __forceinline__ void p0_prologue(const Args& a, LAS unsigned char* lds, int vcu, int G, int tid, int lane, int wave) {
;     ...
;     for (int qq = 0; qq < 2; ++qq) { const int m = m0 + qq * NGW; if (m >= MT) break;
;         rms_row_to_bf16(xrow_ptr(a, m, z), (const float*)a.in[I_F1PRE + z], (bf16*)(ws + WS_XN) + (size_t)m * DM, lane);
.Lp0a_fin:
	v_lshl_add_u64 v[2:3], v[16:17], 0, s[2:3]
	s_cmpk_gt_i32 s6, 0x40ff
	global_store_dwordx2 v[2:3], v[0:1], off
	s_cbranch_scc1 .LBB0_41
	s_cmpk_gt_i32 s6, 0x3fff
	s_cselect_b64 s[10:11], -1, 0
	s_cmpk_lt_i32 s6, 0x4000
	s_mov_b64 s[2:3], -1
	s_cbranch_scc1 .LBB0_67
	s_mov_b64 s[2:3], 0
	s_cmpk_gt_u32 s6, 0x407f
	s_mov_b64 s[12:13], 0
	s_cbranch_scc1 .LBB0_67
	s_load_dwordx2 s[12:13], s[4:5], 0x8
	s_add_i32 s8, s6, 0xffffc000
	s_lshl_b64 s[14:15], s[8:9], 12
	s_waitcnt lgkmcnt(0)
	s_add_u32 s12, s12, s14
	s_addc_u32 s13, s13, s15

; __device__ __forceinline__ unsigned pk2(float lo, float hi) { f32x2 v = {lo, hi}; bf16x2_t b = __builtin_convertvector(v, bf16x2_t); return __builtin_bit_cast(unsigned, b); }
; __device__ __forceinline__ void rms_row_to_bf16(const float* xrow, const float* gain, bf16* orow, int lane) {
;     f32x4 v[4]; float s = 0.f;
; #pragma unroll
;     for (int j = 0; j < 4; ++j) { v[j] = xrow ? ((const f32x4*)xrow)[lane + 64 * j] : (f32x4){0.f, 0.f, 0.f, 0.f}; s += (v[j].x * v[j].x + v[j].y * v[j].y) + (v[j].z * v[j].z + v[j].w * v[j].w); }
;     const float rstd = 1.f / sqrtf(wave_sum(s) * (1.f / DM) + EPS);
; #pragma unroll
;     for (int j = 0; j < 4; ++j) { const f32x4 g = ((const f32x4*)gain)[lane + 64 * j];
;         u32x2 o; o.x = pk2(v[j].x * rstd * g.x, v[j].y * rstd * g.y); o.y = pk2(v[j].z * rstd * g.z, v[j].w * rstd * g.w);
;         ((u32x2*)orow)[lane + 64 * j] = o; }
; __device__ __forceinline__ void p0_prologue(const Args& a, LAS unsigned char* lds, int vcu, int G, int tid, int lane, int wave) {
;     ...
;         const float* pr = m < MP ? (const float*)a.in[I_PP + z] + (size_t)m * DPLE : (m < MP + NS ? (const float*)a.in[I_PS + z] + (size_t)(m - MP) * DPLE : nullptr);
;         const f32x4 v = pr ? ((const f32x4*)pr)[lane] : (f32x4){0.f, 0.f, 0.f, 0.f};
;         u32x2 o; o.x = pk2(v.x, v.y); o.y = pk2(v.z, v.w);
;         ((u32x2*)((bf16*)(ws + WS_PB) + (size_t)m * DPLE))[lane] = o;
.Lp0b_nopf:
	s_load_dwordx2 s[12:13], s[4:5], 0x48
	s_waitcnt vmcnt(0)
	v_mul_f32_e32 v25, v9, v9
	v_mul_f32_e32 v30, v11, v11
	v_mul_f32_e32 v31, v1, v1
	v_mul_f32_e32 v32, v3, v3
	s_waitcnt lgkmcnt(0)
	v_mov_b64_e32 v[26:27], v[40:41]
	v_mov_b64_e32 v[28:29], v[42:43]
	v_mul_f32_e32 v33, v13, v13
	v_mul_f32_e32 v34, v15, v15
	v_fmac_f32_e32 v25, v8, v8
	v_fmac_f32_e32 v30, v10, v10
	v_fmac_f32_e32 v31, v0, v0
	v_fmac_f32_e32 v32, v2, v2
	v_mul_f32_e32 v35, v5, v5
	v_mul_f32_e32 v36, v7, v7
	v_fmac_f32_e32 v33, v12, v12
	v_fmac_f32_e32 v34, v14, v14
	v_add_f32_e32 v25, v25, v30
	v_add_f32_e32 v30, v31, v32
	v_fmac_f32_e32 v35, v4, v4
	v_fmac_f32_e32 v36, v6, v6
	v_add_f32_e32 v31, v33, v34
	v_add_f32_e32 v25, v25, v30
	v_add_f32_e32 v32, v35, v36
	v_add_f32_e32 v25, v25, v31
	v_add_f32_e32 v25, v25, v32
	s_ashr_i32 s7, s6, 31
	s_lshl_b64 s[14:15], s[6:7], 11
	v_add_f32_dpp v25, v25, v25 quad_perm:[1,0,3,2] row_mask:0xf bank_mask:0xf bound_ctrl:1
	s_nop 1
	v_add_f32_dpp v25, v25, v25 quad_perm:[2,3,0,1] row_mask:0xf bank_mask:0xf bound_ctrl:1
	s_nop 1
	v_add_f32_dpp v25, v25, v25 row_half_mirror row_mask:0xf bank_mask:0xf bound_ctrl:1
	s_nop 1
	v_add_f32_dpp v25, v25, v25 row_mirror row_mask:0xf bank_mask:0xf bound_ctrl:1
	v_mov_b32_e32 v30, v25
	s_nop 1
	v_permlane16_swap_b32_e32 v25, v30
	v_add_f32_e32 v25, v25, v30
	v_mov_b32_e32 v30, v25
	s_nop 1
	v_permlane32_swap_b32_e32 v25, v30
	v_add_f32_e32 v25, v25, v30
	v_fmamk_f32 v25, v25, 0x3a800000, v22
	v_mul_f32_e32 v30, 0x4f800000, v25
	v_cmp_gt_f32_e32 vcc, s16, v25
	s_nop 1
	v_cndmask_b32_e32 v25, v25, v30, vcc
	v_sqrt_f32_e32 v30, v25
	s_nop 0
	v_add_u32_e32 v31, -1, v30
	v_add_u32_e32 v32, 1, v30
	v_fma_f32 v33, -v31, v30, v25
	v_fma_f32 v34, -v32, v30, v25
	v_cmp_ge_f32_e64 s[2:3], 0, v33
	s_nop 1
	v_cndmask_b32_e64 v30, v30, v31, s[2:3]
	v_cmp_lt_f32_e64 s[2:3], 0, v34
	s_nop 1
	v_cndmask_b32_e64 v30, v30, v32, s[2:3]
	v_mul_f32_e32 v31, 0x37800000, v30
	v_cndmask_b32_e32 v30, v30, v31, vcc
	v_cmp_class_f32_e32 vcc, v25, v23
	s_nop 1
	v_cndmask_b32_e32 v25, v30, v25, vcc
	v_div_scale_f32 v32, s[2:3], v25, v25, 1.0
	v_rcp_f32_e32 v33, v32
	v_div_scale_f32 v34, vcc, 1.0, v25, 1.0
	v_lshl_add_u64 v[30:31], v[20:21], 0, s[14:15]
	v_fma_f32 v35, -v32, v33, 1.0
	v_fmac_f32_e32 v33, v35, v33
	v_mul_f32_e32 v35, v34, v33
	v_fma_f32 v36, -v32, v35, v34
	v_fmac_f32_e32 v35, v36, v33
	v_fma_f32 v32, -v32, v35, v34
	v_div_fmas_f32 v32, v32, v33, v35
	v_div_fixup_f32 v32, v32, v25, 1.0
	v_pk_mul_f32 v[8:9], v[8:9], v[32:33] op_sel_hi:[1,0]
	v_pk_mul_f32 v[10:11], v[10:11], v[32:33] op_sel_hi:[1,0]
	v_pk_mul_f32 v[8:9], v[26:27], v[8:9]
	v_pk_mul_f32 v[10:11], v[28:29], v[10:11]
	v_cvt_pk_bf16_f32 v8, v8, v9
	v_cvt_pk_bf16_f32 v9, v10, v11
	global_store_dwordx2 v[30:31], v[8:9], off
	s_nop 0
	v_mov_b64_e32 v[8:9], v[44:45]
	v_mov_b64_e32 v[10:11], v[46:47]
	v_pk_mul_f32 v[0:1], v[0:1], v[32:33] op_sel_hi:[1,0]
	v_pk_mul_f32 v[2:3], v[2:3], v[32:33] op_sel_hi:[1,0]
	v_pk_mul_f32 v[4:5], v[4:5], v[32:33] op_sel_hi:[1,0]
	v_pk_mul_f32 v[6:7], v[6:7], v[32:33] op_sel_hi:[1,0]
	s_andn2_b64 vcc, exec, s[10:11]
	s_mov_b64 s[10:11], -1
	v_pk_mul_f32 v[0:1], v[8:9], v[0:1]
	v_pk_mul_f32 v[2:3], v[10:11], v[2:3]
	v_cvt_pk_bf16_f32 v0, v0, v1
	v_cvt_pk_bf16_f32 v1, v2, v3
	global_store_dwordx2 v[30:31], v[0:1], off offset:512
	s_nop 0
	v_mov_b64_e32 v[0:1], v[48:49]
	v_mov_b64_e32 v[2:3], v[50:51]
	v_pk_mul_f32 v[8:9], v[12:13], v[32:33] op_sel_hi:[1,0]
	v_pk_mul_f32 v[10:11], v[14:15], v[32:33] op_sel_hi:[1,0]
	v_pk_mul_f32 v[0:1], v[0:1], v[8:9]
	v_pk_mul_f32 v[2:3], v[2:3], v[10:11]
	v_cvt_pk_bf16_f32 v0, v0, v1
	v_cvt_pk_bf16_f32 v1, v2, v3
	global_store_dwordx2 v[30:31], v[0:1], off offset:1024
	s_nop 0
	v_mov_b64_e32 v[0:1], v[52:53]
	v_mov_b64_e32 v[2:3], v[54:55]
	v_pk_mul_f32 v[0:1], v[4:5], v[0:1]
	v_pk_mul_f32 v[2:3], v[6:7], v[2:3]
	v_cvt_pk_bf16_f32 v0, v0, v1
	v_cvt_pk_bf16_f32 v1, v2, v3
	global_store_dwordx2 v[30:31], v[0:1], off offset:1536
	s_cmpk_gt_i32 s6, 0x3fff
	s_cbranch_scc1 .Lp0b_orig
	v_cvt_pk_bf16_f32 v0, v56, v57
	v_cvt_pk_bf16_f32 v1, v58, v59
	s_lshl_b64 s[2:3], s[6:7], 9
	s_branch .Lp0b_fin
.Lp0b_orig:
	s_cbranch_vccnz .LBB0_80
	s_mov_b64 s[10:11], 0
	s_cmpk_gt_u32 s6, 0x407f
	s_mov_b64 s[2:3], 0
	s_cbranch_scc1 .LBB0_80
	s_load_dwordx2 s[2:3], s[4:5], 0x18
	s_add_i32 s8, s6, 0xffffc000
	s_lshl_b64 s[12:13], s[8:9], 10
	s_waitcnt lgkmcnt(0)
	s_add_u32 s2, s2, s12
	s_addc_u32 s3, s3, s13
